# code warm-up: at 9 in-loop seams wave 1 touches the next phase's code range with data loads (L2 warm for instruction fetch) while waiting at the closing barrier
# speedup vs baseline: 1.0057x; 1.0049x over previous
.LBB0_414:
	s_or_b64 exec, exec, s[0:1]
	v_readlane_b32 s0, v238, 0
	s_cmp_lg_u32 s0, 1
	s_cbranch_scc1 .Lcw_skip_0
	v_and_b32_e32 v204, 63, v0
	v_lshlrev_b32_e32 v204, 7, v204
	s_getpc_b64 s[0:1]
.Lcw_pc_0_0:
	s_add_u32 s0, s0, (.LBB0_415-.Lcw_pc_0_0)&4294967295
	s_addc_u32 s1, s1, (.LBB0_415-.Lcw_pc_0_0)>>32
	s_mov_b32 s10, (.LBB0_618-.LBB0_415)>>13
	s_cmp_eq_u32 s10, 0
	s_cbranch_scc1 .Lcw_done_0_0
.Lcw_loop_0_0:
	global_load_dword v205, v204, s[0:1]
	s_add_u32 s0, s0, 0x2000
	s_addc_u32 s1, s1, 0
	s_sub_u32 s10, s10, 1
	s_cmp_lg_u32 s10, 0
	s_cbranch_scc1 .Lcw_loop_0_0

.Lcw_skip_0:
	s_waitcnt lgkmcnt(0)
	s_barrier

.Lcw_done_8_0:
	s_getpc_b64 s[0:1]
